# strategy 4 on the attention unit loop too: static s_setprio 1 for waves 4-7, reset at loop exit (prep raise kept)
# baseline (speedup 1.0000x reference)
.LBB0_380:
	s_cmp_lt_i32 s34, 6
	s_cselect_b64 s[8:9], -1, 0
	v_writelane_b32 v255, s8, 2
	s_and_b64 s[6:7], s[8:9], s[6:7]
	s_andn2_b64 vcc, exec, s[6:7]
	v_writelane_b32 v255, s9, 3
	s_cbranch_vccnz .LBB0_571
	s_cmp_gt_i32 s2, 31
	s_cbranch_scc0 .LBB0_403
	v_and_b32_e32 v1, 63, v0
	v_and_b32_e32 v14, 15, v1
	v_lshrrev_b32_e32 v5, 4, v1
	v_xor_b32_e32 v11, 16, v1
	v_lshlrev_b32_e32 v11, 2, v11
	v_xor_b32_e32 v12, 32, v1
	v_lshlrev_b32_e32 v12, 2, v12
	v_lshlrev_b32_e32 v13, 11, v14
	v_lshl_add_u32 v13, v5, 4, v13
	v_lshlrev_b32_e32 v15, 4, v5
	v_lshlrev_b32_e32 v6, 2, v5
	v_sub_u32_e32 v7, v14, v6
	v_add_u32_e32 v7, 0x90, v7
	v_cvt_f32_i32_e32 v16, v7
	v_lshlrev_b32_e32 v17, 13, v5
	v_lshl_add_u32 v17, v14, 1, v17
	v_add_u32_e32 v18, 0x1000, v17
	v_lshlrev_b32_e32 v19, 6, v14
	v_lshl_add_u32 v19, v5, 4, v19
	v_mov_b32_e32 v20, v6
	v_mov_b32_e32 v133, 0xf149f2ca
	v_add_u32_e32 v7, 0, v6
	v_cmp_lt_u32_e64 s[74:75], v14, v7
	v_cmp_ge_u32_e64 s[82:83], v14, v7
	v_add_u32_e32 v7, 1, v6
	v_cmp_lt_u32_e64 s[76:77], v14, v7
	v_cmp_ge_u32_e64 s[84:85], v14, v7
	v_add_u32_e32 v7, 2, v6
	v_cmp_lt_u32_e64 s[78:79], v14, v7
	v_cmp_ge_u32_e64 s[86:87], v14, v7
	v_add_u32_e32 v7, 3, v6
	v_cmp_lt_u32_e64 s[80:81], v14, v7
	v_cmp_ge_u32_e64 s[88:89], v14, v7
	s_load_dword s6, s[0:1], 0xd8
	v_readfirstlane_b32 s7, v130
	s_sub_u32 s3, s2, 32
	s_lshl_b32 s3, s3, 3
	s_nop 0
	s_add_u32 s3, s3, s7
	s_waitcnt lgkmcnt(0)
	s_sub_u32 s6, s6, 32
	s_lshl_b32 s6, s6, 3
	s_cmp_lt_u32 s7, 4
	s_cbranch_scc1 .Lat_noprio
	s_setprio 1
.Lat_noprio:
.Lat_loop:
	s_and_b32 s27, s3, 15
	s_bfe_u32 s28, s3, 0x80004
	s_lshr_b32 s29, s3, 12
	s_lshr_b32 s30, s27, 2
	s_lshl_b32 s31, s28, 4
	s_lshl_b32 s93, s27, 2
	s_load_dword s26, s[44:45], s93
	s_lshl_b32 s90, s29, 12
	s_add_u32 s90, s90, s31
	s_lshl_b32 s91, s90, 11
	s_lshl_b32 s92, s27, 7
	s_add_u32 s91, s91, s92
	s_add_u32 s8, s68, s91
	s_addc_u32 s9, s69, 0
	s_add_u32 s8, s8, 0x3000000
	s_addc_u32 s9, s9, 0
	s_add_u32 s20, s70, s91
	s_addc_u32 s21, s71, 0
	s_add_u32 s20, s20, 0x13900000
	s_addc_u32 s21, s21, 0
	s_lshl_b32 s94, s29, 2
	s_add_u32 s94, s94, s30
	s_lshl_b32 s94, s94, 19
	s_add_u32 s10, s70, s94
	s_addc_u32 s11, s71, 0
	s_add_u32 s10, s10, 0x13100000
	s_addc_u32 s11, s11, 0
	s_lshl_b32 s94, s29, 2
	s_add_u32 s94, s94, s30
	s_lshl_b32 s94, s94, 19
	s_add_u32 s12, s70, s94
	s_addc_u32 s13, s71, 0
	s_add_u32 s12, s12, 0x13500000
	s_addc_u32 s13, s13, 0
	s_add_i32 s22, s31, 0xffffff70
	s_sub_i32 s23, 9, s28
	s_max_i32 s23, s23, 0
	s_add_u32 s24, s27, 1
	v_cvt_f32_u32_e32 v21, s24
	v_mul_f32_e32 v21, -0.5, v21
	v_exp_f32_e32 v132, v21
	global_load_dwordx4 v[30:33], v13, s[8:9]
	global_load_dwordx4 v[34:37], v13, s[8:9] offset:64
	s_add_i32 s15, s28, -9
	s_max_i32 s15, s15, 0
	s_lshl_b32 s15, s15, 11
	s_add_u32 s16, s10, s15
	s_addc_u32 s17, s11, 0
	global_load_dwordx4 v[40:43], v19, s[16:17]
	global_load_dwordx4 v[44:47], v19, s[16:17] offset:1024
	s_add_i32 s15, s28, -8
	s_max_i32 s15, s15, 0
	s_lshl_b32 s15, s15, 11
	s_add_u32 s16, s10, s15
	s_addc_u32 s17, s11, 0
	global_load_dwordx4 v[48:51], v19, s[16:17]
	global_load_dwordx4 v[52:55], v19, s[16:17] offset:1024
	s_add_i32 s15, s28, -7
	s_max_i32 s15, s15, 0
	s_lshl_b32 s15, s15, 11
	s_add_u32 s16, s10, s15
	s_addc_u32 s17, s11, 0
	global_load_dwordx4 v[56:59], v19, s[16:17]
	global_load_dwordx4 v[60:63], v19, s[16:17] offset:1024
	s_add_i32 s15, s28, -6
	s_max_i32 s15, s15, 0
	s_lshl_b32 s15, s15, 11
	s_add_u32 s16, s10, s15
	s_addc_u32 s17, s11, 0
	global_load_dwordx4 v[64:67], v19, s[16:17]
	global_load_dwordx4 v[68:71], v19, s[16:17] offset:1024
	s_add_i32 s15, s28, -5
	s_max_i32 s15, s15, 0
	s_lshl_b32 s15, s15, 11
	s_add_u32 s16, s10, s15
	s_addc_u32 s17, s11, 0
	global_load_dwordx4 v[72:75], v19, s[16:17]
	global_load_dwordx4 v[76:79], v19, s[16:17] offset:1024
	s_add_i32 s15, s28, -4
	s_max_i32 s15, s15, 0
	s_lshl_b32 s15, s15, 11
	s_add_u32 s16, s10, s15
	s_addc_u32 s17, s11, 0
	global_load_dwordx4 v[80:83], v19, s[16:17]
	global_load_dwordx4 v[84:87], v19, s[16:17] offset:1024
	s_add_i32 s15, s28, -3
	s_max_i32 s15, s15, 0
	s_lshl_b32 s15, s15, 11
	s_add_u32 s16, s10, s15
	s_addc_u32 s17, s11, 0
	global_load_dwordx4 v[88:91], v19, s[16:17]
	global_load_dwordx4 v[92:95], v19, s[16:17] offset:1024
	s_add_i32 s15, s28, -2
	s_max_i32 s15, s15, 0
	s_lshl_b32 s15, s15, 11
	s_add_u32 s16, s10, s15
	s_addc_u32 s17, s11, 0
	global_load_dwordx4 v[96:99], v19, s[16:17]
	global_load_dwordx4 v[100:103], v19, s[16:17] offset:1024
	s_add_i32 s15, s28, -1
	s_max_i32 s15, s15, 0
	s_lshl_b32 s15, s15, 11
	s_add_u32 s16, s10, s15
	s_addc_u32 s17, s11, 0
	global_load_dwordx4 v[104:107], v19, s[16:17]
	global_load_dwordx4 v[108:111], v19, s[16:17] offset:1024
	s_add_i32 s15, s28, 0
	s_max_i32 s15, s15, 0
	s_lshl_b32 s15, s15, 11
	s_add_u32 s16, s10, s15
	s_addc_u32 s17, s11, 0
	global_load_dwordx4 v[112:115], v19, s[16:17]
	global_load_dwordx4 v[116:119], v19, s[16:17] offset:1024
	s_add_i32 s14, s28, -8
	s_ashr_i32 s14, s14, 1
	s_add_i32 s15, s14, 0
	s_max_i32 s15, s15, 0
	s_min_i32 s15, s15, 0x7f
	s_lshl_b32 s15, s15, 12
	s_add_u32 s16, s12, s15
	s_addc_u32 s17, s13, 0
	global_load_dwordx4 v[160:163], v19, s[16:17]
	global_load_dwordx4 v[164:167], v19, s[16:17] offset:1024
	global_load_dwordx4 v[168:171], v19, s[16:17] offset:2048
	global_load_dwordx4 v[172:175], v19, s[16:17] offset:3072
	s_add_i32 s15, s14, 1
	s_max_i32 s15, s15, 0
	s_min_i32 s15, s15, 0x7f
	s_lshl_b32 s15, s15, 12
	s_add_u32 s16, s12, s15
	s_addc_u32 s17, s13, 0
	global_load_dwordx4 v[176:179], v19, s[16:17]
	global_load_dwordx4 v[180:183], v19, s[16:17] offset:1024
	global_load_dwordx4 v[184:187], v19, s[16:17] offset:2048
	global_load_dwordx4 v[188:191], v19, s[16:17] offset:3072
	s_add_i32 s15, s14, 2
	s_max_i32 s15, s15, 0
	s_min_i32 s15, s15, 0x7f
	s_lshl_b32 s15, s15, 12
	s_add_u32 s16, s12, s15
	s_addc_u32 s17, s13, 0
	global_load_dwordx4 v[192:195], v19, s[16:17]
	global_load_dwordx4 v[196:199], v19, s[16:17] offset:1024
	global_load_dwordx4 v[200:203], v19, s[16:17] offset:2048
	global_load_dwordx4 v[204:207], v19, s[16:17] offset:3072
	s_add_i32 s15, s14, 3
	s_max_i32 s15, s15, 0
	s_min_i32 s15, s15, 0x7f
	s_lshl_b32 s15, s15, 12
	s_add_u32 s16, s12, s15
	s_addc_u32 s17, s13, 0
	global_load_dwordx4 v[208:211], v19, s[16:17]
	global_load_dwordx4 v[212:215], v19, s[16:17] offset:1024
	global_load_dwordx4 v[216:219], v19, s[16:17] offset:2048
	global_load_dwordx4 v[220:223], v19, s[16:17] offset:3072
	s_add_i32 s15, s14, 4
	s_max_i32 s15, s15, 0
	s_min_i32 s15, s15, 0x7f
	s_lshl_b32 s15, s15, 12
	s_add_u32 s16, s12, s15
	s_addc_u32 s17, s13, 0
	global_load_dwordx4 v[224:227], v19, s[16:17]
	global_load_dwordx4 v[228:231], v19, s[16:17] offset:1024
	global_load_dwordx4 v[232:235], v19, s[16:17] offset:2048
	global_load_dwordx4 v[236:239], v19, s[16:17] offset:3072
	v_sub_f32_e32 v132, 0, v132
	s_waitcnt lgkmcnt(0)
	v_mov_b32_e32 v128, s26
	s_waitcnt vmcnt(38)
	v_mfma_f32_16x16x32_bf16 v[40:43], v[40:43], v[30:33], 0
	v_mfma_f32_16x16x32_bf16 v[40:43], v[44:47], v[34:37], v[40:43]
	s_waitcnt vmcnt(36)
	v_mfma_f32_16x16x32_bf16 v[48:51], v[48:51], v[30:33], 0
	v_mfma_f32_16x16x32_bf16 v[48:51], v[52:55], v[34:37], v[48:51]
	s_waitcnt vmcnt(34)
	v_mfma_f32_16x16x32_bf16 v[56:59], v[56:59], v[30:33], 0
	v_mfma_f32_16x16x32_bf16 v[56:59], v[60:63], v[34:37], v[56:59]
	s_waitcnt vmcnt(32)
	v_mfma_f32_16x16x32_bf16 v[64:67], v[64:67], v[30:33], 0
	v_mfma_f32_16x16x32_bf16 v[64:67], v[68:71], v[34:37], v[64:67]
	s_waitcnt vmcnt(30)
	v_mfma_f32_16x16x32_bf16 v[72:75], v[72:75], v[30:33], 0
	v_mfma_f32_16x16x32_bf16 v[72:75], v[76:79], v[34:37], v[72:75]
	s_waitcnt vmcnt(28)
	v_mfma_f32_16x16x32_bf16 v[80:83], v[80:83], v[30:33], 0
	v_mfma_f32_16x16x32_bf16 v[80:83], v[84:87], v[34:37], v[80:83]
	s_waitcnt vmcnt(26)
	v_mfma_f32_16x16x32_bf16 v[88:91], v[88:91], v[30:33], 0
	v_mfma_f32_16x16x32_bf16 v[88:91], v[92:95], v[34:37], v[88:91]
	s_waitcnt vmcnt(24)
	v_mfma_f32_16x16x32_bf16 v[96:99], v[96:99], v[30:33], 0
	v_mfma_f32_16x16x32_bf16 v[96:99], v[100:103], v[34:37], v[96:99]
	s_waitcnt vmcnt(22)
	v_mfma_f32_16x16x32_bf16 v[104:107], v[104:107], v[30:33], 0
	v_mfma_f32_16x16x32_bf16 v[104:107], v[108:111], v[34:37], v[104:107]
	s_waitcnt vmcnt(20)
	v_mfma_f32_16x16x32_bf16 v[112:115], v[112:115], v[30:33], 0
	v_mfma_f32_16x16x32_bf16 v[112:115], v[116:119], v[34:37], v[112:115]
	v_mov_b32_e32 v40, v133
	v_mov_b32_e32 v41, v133
	v_mov_b32_e32 v42, v133
	v_mov_b32_e32 v43, v133
	v_subrev_f32_e32 v21, 0x41800000, v16
	v_subrev_f32_e32 v22, 0x41880000, v16
	v_subrev_f32_e32 v23, 0x41900000, v16
	v_subrev_f32_e32 v24, 0x41980000, v16
	v_fma_f32 v48, v132, v21, v48
	v_fma_f32 v49, v132, v22, v49
	v_fma_f32 v50, v132, v23, v50
	v_fma_f32 v51, v132, v24, v51
	v_cndmask_b32_e64 v48, v133, v48, s[74:75]
	v_cndmask_b32_e64 v49, v133, v49, s[76:77]
	v_cndmask_b32_e64 v50, v133, v50, s[78:79]
	v_cndmask_b32_e64 v51, v133, v51, s[80:81]
	s_cmp_lt_u32 s23, 2
	s_cbranch_scc1 .Lat_ok_1
	v_mov_b32_e32 v48, v133
	v_mov_b32_e32 v49, v133
	v_mov_b32_e32 v50, v133
	v_mov_b32_e32 v51, v133

.Lat_pv_done:
	s_nop 7
	v_cvt_pk_bf16_f32 v22, v240, v240
	v_cvt_pk_bf16_f32 v23, v241, v241
	v_cvt_pk_bf16_f32 v24, v242, v242
	v_cvt_pk_bf16_f32 v25, v243, v243
	v_cvt_pk_bf16_f32 v26, v244, v244
	v_cvt_pk_bf16_f32 v27, v245, v245
	v_cvt_pk_bf16_f32 v28, v246, v246
	v_cvt_pk_bf16_f32 v29, v247, v247
	v_cvt_pk_bf16_f32 v134, v248, v248
	v_cvt_pk_bf16_f32 v135, v249, v249
	v_cvt_pk_bf16_f32 v136, v250, v250
	v_cvt_pk_bf16_f32 v137, v251, v251
	v_cvt_pk_bf16_f32 v138, v120, v120
	v_cvt_pk_bf16_f32 v139, v121, v121
	v_cvt_pk_bf16_f32 v150, v122, v122
	v_cvt_pk_bf16_f32 v151, v123, v123
	global_store_short v17, v22, s[20:21]
	global_store_short v17, v23, s[20:21] offset:2048
	global_store_short v18, v24, s[20:21]
	global_store_short v18, v25, s[20:21] offset:2048
	global_store_short v17, v26, s[20:21] offset:32
	global_store_short v17, v27, s[20:21] offset:2080
	global_store_short v18, v28, s[20:21] offset:32
	global_store_short v18, v29, s[20:21] offset:2080
	global_store_short v17, v134, s[20:21] offset:64
	global_store_short v17, v135, s[20:21] offset:2112
	global_store_short v18, v136, s[20:21] offset:64
	global_store_short v18, v137, s[20:21] offset:2112
	global_store_short v17, v138, s[20:21] offset:96
	global_store_short v17, v139, s[20:21] offset:2144
	global_store_short v18, v150, s[20:21] offset:96
	global_store_short v18, v151, s[20:21] offset:2144
	s_add_u32 s3, s3, s6
	s_cmp_lt_u32 s3, 0x2000
	s_cbranch_scc1 .Lat_loop
	s_setprio 0
	v_and_b32_e32 v10, 15, v0
	s_add_u32 s74, s0, 0xd8
	s_addc_u32 s75, s1, 0
	v_mov_b64_e32 v[2:3], s[74:75]
	s_mov_b64 s[64:65], exec
	s_nop 0
	s_nop 0
	s_nop 0
	s_nop 0
	s_nop 0
	s_nop 0
	s_nop 0
	s_nop 0
	s_nop 0
	s_nop 0
	s_nop 0
